# diff-attn loop: 8-slot V fragment pipeline, barrier 1 moved inside PV, staging ds_writes hidden under last PV MFMAs
# speedup vs baseline: 1.0027x; 1.0027x over previous
; __device__ __forceinline__ void finishSM(f32x16& p0, f32x16& p1, float alpha, float& l_reg, bf16x8& pa0, bf16x8& pa1, bf16x8& pa2, bf16x8& pa3) {
;     for (int r = 0; r < 16; ++r) p1[r] = __builtin_amdgcn_exp2f(p1[r]);
;     float ps = 0; for (int r = 0; r < 16; ++r) ps += p0[r]; for (int r = 0; r < 16; ++r) ps += p1[r];
;     { auto rr = __builtin_amdgcn_permlane32_swap(__float_as_uint(ps), __float_as_uint(ps), false, false);
;       ps = __uint_as_float(rr[0]) + __uint_as_float(rr[1]); }
;     l_reg = l_reg * alpha + ps;
;     ...
;     PK4(p0, 0, pa0); PK4(p0, 8, pa1); PK4(p1, 0, pa2); PK4(p1, 8, pa3);
;     ...
; }
; template <int KB, bool SK>
; __device__ __forceinline__ void qkt(f32x16& p0, f32x16& p1, const char* K_lds, int r32, int hi, const bf16x8* qr, bool act) {
;     if (SK && !act) { const float NEG = -__builtin_inff();
; #pragma unroll
;         for (int r = 0; r < 16; ++r) { p0[r] = NEG; p1[r] = NEG; } return; }
;     p0 = f32x16{}; p1 = f32x16{};
;     const char* kb[4];
; #pragma unroll
;     for (int dd = 0; dd < 4; ++dd) kb[dd] = K_lds + KB * SHM_K + KSWZ(r32, (dd * 16 + hi * 8) * 2);
; #pragma unroll
;     for (int d0 = 0; d0 < 8; ++d0) { const char* a = kb[d0 & 3] + (d0 >> 2) * 128;
;         bf16x8 b0 = *reinterpret_cast<const bf16x8*>(a);
;         bf16x8 b1 = *reinterpret_cast<const bf16x8*>(a + 32 * 256);
;         const bf16x8 qf = qr[d0];
;         p0 = __builtin_amdgcn_mfma_f32_32x32x16_bf16(b0, qf, p0, 0, 0, 0);
;         p1 = __builtin_amdgcn_mfma_f32_32x32x16_bf16(b1, qf, p1, 0, 0, 0); }
; }
; template <int VB, bool SK>
; __device__ __forceinline__ void pv_tile(f32x16* o, int vb0, bf16x8 pa0, bf16x8 pa1, bf16x8 pa2, bf16x8 pa3, bool act) {
;     ...
;     PV_D0(0); PV_D0(1); PV_D0(2); PV_D0(3);
.LBB0_1129:
	ds_read_b128 v[180:183], v211 offset:49152
	ds_read_b128 v[184:187], v211 offset:57344
	ds_read_b128 v[188:191], v212 offset:49152
	ds_read_b128 v[228:231], v212 offset:57344
	ds_read_b128 v[232:235], v213 offset:49152
	ds_read_b128 v[236:239], v213 offset:57344
	ds_read_b128 v[240:243], v214 offset:49152
	ds_read_b128 v[244:247], v214 offset:57344
	v_exp_f32_e32 v126, v126
	v_exp_f32_e32 v127, v127
	v_exp_f32_e32 v124, v124
	v_exp_f32_e32 v125, v125
	v_exp_f32_e32 v120, v120
	v_exp_f32_e32 v121, v121
	v_exp_f32_e32 v116, v116
	v_exp_f32_e32 v117, v117
	v_exp_f32_e32 v114, v114
	v_exp_f32_e32 v115, v115
	v_exp_f32_e32 v128, v128
	v_exp_f32_e32 v129, v129
	v_exp_f32_e32 v122, v122
	v_exp_f32_e32 v123, v123
	v_exp_f32_e32 v118, v118
	v_exp_f32_e32 v119, v119
	s_add_i32 s4, s26, 0xffffff81
	s_sub_i32 s5, s26, 64
	s_waitcnt lgkmcnt(7)
	v_mfma_f32_32x32x16_bf16 v[86:101], v[180:183], v[158:161], 0
	ds_read_b128 v[180:183], v211 offset:49280
	v_add_f32_e32 v179, 0, v170
	v_add_f32_e32 v179, v171, v179
	v_add_f32_e32 v179, v172, v179
	v_add_f32_e32 v179, v173, v179
	s_waitcnt lgkmcnt(7)
	v_mfma_f32_32x32x16_bf16 v[70:85], v[184:187], v[158:161], 0
	ds_read_b128 v[184:187], v211 offset:57472
	v_add_f32_e32 v179, v174, v179
	v_add_f32_e32 v179, v176, v179
	v_add_f32_e32 v179, v175, v179
	v_add_f32_e32 v179, v177, v179
	s_waitcnt lgkmcnt(7)
	v_mfma_f32_32x32x16_bf16 v[86:101], v[188:191], v[154:157], v[86:101]
	ds_read_b128 v[188:191], v212 offset:49280
	v_add_f32_e32 v179, v162, v179
	v_add_f32_e32 v179, v163, v179
	v_add_f32_e32 v110, v164, v179
	v_add_f32_e32 v110, v166, v110
	s_waitcnt lgkmcnt(7)
	v_mfma_f32_32x32x16_bf16 v[70:85], v[228:231], v[154:157], v[70:85]
	ds_read_b128 v[228:231], v212 offset:57472
	v_add_f32_e32 v110, v165, v110
	v_add_f32_e32 v110, v167, v110
	v_add_f32_e32 v110, v168, v110
	v_add_f32_e32 v110, v169, v110
	s_waitcnt lgkmcnt(7)
	v_mfma_f32_32x32x16_bf16 v[86:101], v[232:235], v[150:153], v[86:101]
	ds_read_b128 v[232:235], v213 offset:49280
	v_add_f32_e32 v110, v126, v110
	v_add_f32_e32 v102, v127, v110
	v_add_f32_e32 v102, v124, v102
	v_add_f32_e32 v102, v125, v102
	s_waitcnt lgkmcnt(7)
	v_mfma_f32_32x32x16_bf16 v[70:85], v[236:239], v[150:153], v[70:85]
	ds_read_b128 v[236:239], v213 offset:57472
	v_add_f32_e32 v102, v120, v102
	v_add_f32_e32 v102, v121, v102
	v_add_f32_e32 v102, v116, v102
	v_add_f32_e32 v102, v117, v102
	s_waitcnt lgkmcnt(7)
	v_mfma_f32_32x32x16_bf16 v[86:101], v[240:243], v[134:137], v[86:101]
	ds_read_b128 v[240:243], v214 offset:49280
	v_add_f32_e32 v102, v114, v102
	v_add_f32_e32 v102, v115, v102
	v_add_f32_e32 v102, v128, v102
	v_add_f32_e32 v102, v129, v102
	s_waitcnt lgkmcnt(7)
	v_mfma_f32_32x32x16_bf16 v[70:85], v[244:247], v[134:137], v[70:85]
	ds_read_b128 v[244:247], v214 offset:57472
	v_add_f32_e32 v102, v122, v102
	v_add_f32_e32 v102, v123, v102
	v_add_f32_e32 v102, v118, v102
	v_add_f32_e32 v223, v119, v102
	s_waitcnt lgkmcnt(7)
	v_mfma_f32_32x32x16_bf16 v[86:101], v[180:183], v[138:141], v[86:101]
	v_mov_b32_e32 v224, v223
	s_nop 1
	v_permlane32_swap_b32_e32 v223, v224
	v_cvt_pk_bf16_f32 v102, v170, v171
	v_cvt_pk_bf16_f32 v103, v172, v173
	s_waitcnt lgkmcnt(6)
	v_mfma_f32_32x32x16_bf16 v[70:85], v[184:187], v[138:141], v[70:85]
	v_cvt_pk_bf16_f32 v104, v174, v176
	v_cvt_pk_bf16_f32 v105, v175, v177
	v_cvt_pk_bf16_f32 v66, v162, v163
	v_cvt_pk_bf16_f32 v67, v164, v166
	s_waitcnt lgkmcnt(5)
	v_mfma_f32_32x32x16_bf16 v[86:101], v[188:191], v[142:145], v[86:101]
	v_cvt_pk_bf16_f32 v68, v165, v167
	v_cvt_pk_bf16_f32 v69, v168, v169
	v_cvt_pk_bf16_f32 v106, v126, v127
	s_waitcnt lgkmcnt(4)
	v_mfma_f32_32x32x16_bf16 v[70:85], v[228:231], v[142:145], v[70:85]
	v_cvt_pk_bf16_f32 v107, v124, v125
	v_cvt_pk_bf16_f32 v108, v120, v121
	v_cvt_pk_bf16_f32 v109, v116, v117
	s_waitcnt lgkmcnt(3)
	v_mfma_f32_32x32x16_bf16 v[86:101], v[232:235], v[146:149], v[86:101]
	v_cvt_pk_bf16_f32 v110, v114, v115
	v_cvt_pk_bf16_f32 v111, v128, v129
	v_cvt_pk_bf16_f32 v112, v122, v123
	s_waitcnt lgkmcnt(2)
	v_mfma_f32_32x32x16_bf16 v[70:85], v[236:239], v[146:149], v[70:85]
	v_cvt_pk_bf16_f32 v113, v118, v119
	s_nop 1
	v_permlane32_swap_b32_e32 v102, v104
	v_permlane32_swap_b32_e32 v103, v105
	s_waitcnt lgkmcnt(1)
	v_mfma_f32_32x32x16_bf16 v[86:101], v[240:243], v[130:133], v[86:101]
	v_permlane32_swap_b32_e32 v66, v68
	v_permlane32_swap_b32_e32 v67, v69
	v_permlane32_swap_b32_e32 v106, v108
	s_waitcnt lgkmcnt(0)
	v_mfma_f32_32x32x16_bf16 v[70:85], v[244:247], v[130:133], v[70:85]
	v_permlane32_swap_b32_e32 v107, v109
	v_permlane32_swap_b32_e32 v110, v112
	v_permlane32_swap_b32_e32 v111, v113
	v_add_u32_e32 v114, 0x2000, v255
	global_load_dwordx4 v[162:165], v255, s[42:43]
	global_load_dwordx4 v[166:169], v114, s[42:43]
	global_load_dwordx4 v[170:173], v255, s[22:23]
	global_load_dwordx4 v[174:177], v114, s[22:23]
	s_cmp_le_i32 s5, s13
	s_cselect_b64 s[52:53], -1, 0
	s_cmp_gt_i32 s4, s15
	s_cselect_b64 s[4:5], -1, 0
	s_and_b64 s[4:5], s[52:53], s[4:5]
	s_and_b64 vcc, exec, s[4:5]
	ds_read_b64_tr_b16 v[114:115], v202 offset:0x0
	ds_read_b64_tr_b16 v[116:117], v202 offset:0x800
	ds_read_b64_tr_b16 v[118:119], v202 offset:0x1000
	ds_read_b64_tr_b16 v[120:121], v202 offset:0x1800
	ds_read_b64_tr_b16 v[122:123], v202 offset:0x2000
	ds_read_b64_tr_b16 v[124:125], v202 offset:0x2800
	ds_read_b64_tr_b16 v[126:127], v202 offset:0x3000
	ds_read_b64_tr_b16 v[128:129], v202 offset:0x3800
	ds_read_b64_tr_b16 v[182:183], v202 offset:0x200
	ds_read_b64_tr_b16 v[184:185], v202 offset:0xa00
	ds_read_b64_tr_b16 v[186:187], v202 offset:0x1200
	ds_read_b64_tr_b16 v[188:189], v202 offset:0x1a00
	ds_read_b64_tr_b16 v[190:191], v202 offset:0x2200
	ds_read_b64_tr_b16 v[192:193], v202 offset:0x2a00
	s_cbranch_vccnz .Lh1_nomask
; __device__ __forceinline__ void mask_tile(f32x16& p0, f32x16& p1, int dq, unsigned W) {
;     const float NEG = -__builtin_inff();
; #pragma unroll
;     for (int r = 0; r < 16; ++r) {
;         const int c = (r & 3) + 8 * (r >> 2);
;         if ((unsigned)(dq - c) >= W) p0[r] = NEG;
;         if ((unsigned)(dq - c - 32) >= W) p1[r] = NEG;
;     }
; }
; __device__ __forceinline__ void partialSM(f32x16& p0, f32x16& p1, float& m_reg, float& mn, float& alpha) {
;     float pmax = p0[0]; for (int r = 1; r < 16; ++r) pmax = fmaxf(pmax, p0[r]); for (int r = 0; r < 16; ++r) pmax = fmaxf(pmax, p1[r]);
;     { auto rr = __builtin_amdgcn_permlane32_swap(__float_as_uint(pmax), __float_as_uint(pmax), false, false);
;       pmax = fmaxf(__uint_as_float(rr[0]), __uint_as_float(rr[1])); }
;     constexpr float C2 = 1.4426950408889634f * SCALE;
;     if (__builtin_expect(__all((pmax - m_reg) * SCALE <= THR), 1)) { mn = m_reg; alpha = 1.f; }
;     else { mn = fmaxf(m_reg, pmax); alpha = __builtin_amdgcn_exp2f((m_reg - mn) * C2); m_reg = mn; }
;     const float mnL = -mn * C2;
;     for (int r = 0; r < 16; ++r) p0[r] = fmaf(p0[r], C2, mnL); for (int r = 0; r < 16; ++r) p1[r] = fmaf(p1[r], C2, mnL);
;     for (int r = 0; r < 16; ++r) p0[r] = __builtin_amdgcn_exp2f(p0[r]);
; }
; template <int VB, bool SK>
; __device__ __forceinline__ void pv_tile(f32x16* o, int vb0, bf16x8 pa0, bf16x8 pa1, bf16x8 pa2, bf16x8 pa3, bool act) {
;     if (SK && !act) return;
;     ...
;     PV_D0(0); PV_D0(1); PV_D0(2); PV_D0(3);
	v_add_u32_e32 v226, s80, v222
	v_subrev_u32_e32 v240, 64, v226
	v_cmp_gt_u32_e32 vcc, s85, v240
	v_add_u32_e32 v240, 0xffffffa0, v226
	s_nop 0
	v_cndmask_b32_e32 v86, v215, v86, vcc
	v_cmp_gt_u32_e32 vcc, s85, v240
	v_add_u32_e32 v240, 0xffffffbf, v226
	s_nop 0
	v_cndmask_b32_e32 v70, v215, v70, vcc
	v_cmp_gt_u32_e32 vcc, s85, v240
	v_add_u32_e32 v240, 0xffffff9f, v226
	s_nop 0
	v_cndmask_b32_e32 v87, v215, v87, vcc
	v_cmp_gt_u32_e32 vcc, s85, v240
	v_add_u32_e32 v240, 0xffffffbe, v226
	s_nop 0
	v_cndmask_b32_e32 v71, v215, v71, vcc
	v_cmp_gt_u32_e32 vcc, s85, v240
	v_add_u32_e32 v240, 0xffffff9e, v226
	s_nop 0
	v_cndmask_b32_e32 v88, v215, v88, vcc
	v_cmp_gt_u32_e32 vcc, s85, v240
	v_add_u32_e32 v240, 0xffffffbd, v226
	s_nop 0
	v_cndmask_b32_e32 v72, v215, v72, vcc
	v_cmp_gt_u32_e32 vcc, s85, v240
	v_add_u32_e32 v240, 0xffffff9d, v226
	s_nop 0
	v_cndmask_b32_e32 v89, v215, v89, vcc
	v_cmp_gt_u32_e32 vcc, s85, v240
	v_add_u32_e32 v240, 0xffffffb8, v226
	s_nop 0
	v_cndmask_b32_e32 v73, v215, v73, vcc
	v_cmp_gt_u32_e32 vcc, s85, v240
	v_add_u32_e32 v240, 0xffffff98, v226
	s_nop 0
	v_cndmask_b32_e32 v90, v215, v90, vcc
	v_cmp_gt_u32_e32 vcc, s85, v240
	v_add_u32_e32 v240, 0xffffffb7, v226
	s_nop 0
	v_cndmask_b32_e32 v74, v215, v74, vcc
	v_cmp_gt_u32_e32 vcc, s85, v240
	v_add_u32_e32 v240, 0xffffff97, v226
	s_nop 0
	v_cndmask_b32_e32 v91, v215, v91, vcc
	v_cmp_gt_u32_e32 vcc, s85, v240
	v_add_u32_e32 v240, 0xffffffb6, v226
	s_nop 0
	v_cndmask_b32_e32 v75, v215, v75, vcc
	v_cmp_gt_u32_e32 vcc, s85, v240
	v_add_u32_e32 v240, 0xffffff96, v226
	s_nop 0
	v_cndmask_b32_e32 v92, v215, v92, vcc
	v_cmp_gt_u32_e32 vcc, s85, v240
	v_add_u32_e32 v240, 0xffffffb5, v226
	s_nop 0
	v_cndmask_b32_e32 v76, v215, v76, vcc
	v_cmp_gt_u32_e32 vcc, s85, v240
	v_add_u32_e32 v240, 0xffffff95, v226
	s_nop 0
	v_cndmask_b32_e32 v93, v215, v93, vcc
	v_cmp_gt_u32_e32 vcc, s85, v240
	v_add_u32_e32 v240, 0xffffffb0, v226
	s_nop 0
	v_cndmask_b32_e32 v77, v215, v77, vcc
	v_cmp_gt_u32_e32 vcc, s85, v240
	v_add_u32_e32 v240, 0xffffff90, v226
	s_nop 0
	v_cndmask_b32_e32 v94, v215, v94, vcc
	v_cmp_gt_u32_e32 vcc, s85, v240
	v_add_u32_e32 v240, 0xffffffaf, v226
	s_nop 0
	v_cndmask_b32_e32 v78, v215, v78, vcc
	v_cmp_gt_u32_e32 vcc, s85, v240
	v_add_u32_e32 v240, 0xffffff8f, v226
	s_nop 0
	v_cndmask_b32_e32 v95, v215, v95, vcc
	v_cmp_gt_u32_e32 vcc, s85, v240
	v_add_u32_e32 v240, 0xffffffae, v226
	s_nop 0
	v_cndmask_b32_e32 v79, v215, v79, vcc
	v_cmp_gt_u32_e32 vcc, s85, v240
	v_add_u32_e32 v240, 0xffffff8e, v226
	s_nop 0
	v_cndmask_b32_e32 v96, v215, v96, vcc
	v_cmp_gt_u32_e32 vcc, s85, v240
	v_add_u32_e32 v240, 0xffffffad, v226
	s_nop 0
	v_cndmask_b32_e32 v80, v215, v80, vcc
	v_cmp_gt_u32_e32 vcc, s85, v240
	v_add_u32_e32 v240, 0xffffff8d, v226
	s_nop 0
	v_cndmask_b32_e32 v97, v215, v97, vcc
	v_cmp_gt_u32_e32 vcc, s85, v240
	v_add_u32_e32 v240, 0xffffffa8, v226
	s_nop 0
	v_cndmask_b32_e32 v81, v215, v81, vcc
	v_cmp_gt_u32_e32 vcc, s85, v240
	v_add_u32_e32 v240, 0xffffff88, v226
	s_nop 0
	v_cndmask_b32_e32 v98, v215, v98, vcc
	v_cmp_gt_u32_e32 vcc, s85, v240
	v_add_u32_e32 v240, 0xffffffa7, v226
	s_nop 0
	v_cndmask_b32_e32 v82, v215, v82, vcc
	v_cmp_gt_u32_e32 vcc, s85, v240
	v_add_u32_e32 v240, 0xffffff87, v226
	s_nop 0
	v_cndmask_b32_e32 v99, v215, v99, vcc
	v_cmp_gt_u32_e32 vcc, s85, v240
	v_add_u32_e32 v240, 0xffffffa6, v226
	s_nop 0
	v_cndmask_b32_e32 v83, v215, v83, vcc
	v_cmp_gt_u32_e32 vcc, s85, v240
	v_add_u32_e32 v240, 0xffffff86, v226
	s_nop 0
	v_cndmask_b32_e32 v100, v215, v100, vcc
	v_cmp_gt_u32_e32 vcc, s85, v240
	v_add_u32_e32 v240, 0xffffffa5, v226
	s_nop 0
	v_cndmask_b32_e32 v84, v215, v84, vcc
	v_cmp_gt_u32_e32 vcc, s85, v240
	v_add_u32_e32 v240, 0xffffff85, v226
	s_nop 0
	v_cndmask_b32_e32 v101, v215, v101, vcc
	v_cmp_gt_u32_e32 vcc, s85, v240
	s_nop 1
	v_cndmask_b32_e32 v85, v215, v85, vcc
.Lh1_nomask:
	v_max_f32_e32 v240, v86, v87
	v_max3_f32 v240, v240, v88, v89
	v_max3_f32 v240, v240, v90, v91
	v_max3_f32 v240, v240, v92, v93
	v_max3_f32 v240, v240, v94, v95
	s_waitcnt lgkmcnt(12)
	v_mfma_f32_32x32x16_bf16 v[34:49], v[102:105], v[114:117], v[34:49]
	ds_read_b64_tr_b16 v[244:245], v202 offset:0x3200
	ds_read_b64_tr_b16 v[246:247], v202 offset:0x3a00
	v_max3_f32 v240, v240, v96, v97
	v_max3_f32 v240, v240, v98, v99
	v_max3_f32 v240, v240, v100, v101
	v_max3_f32 v240, v240, v70, v71
	s_waitcnt lgkmcnt(12)
	v_mfma_f32_32x32x16_bf16 v[34:49], v[66:69], v[118:121], v[34:49]
	ds_read_b64_tr_b16 v[114:115], v202 offset:0x400
	ds_read_b64_tr_b16 v[116:117], v202 offset:0xc00
	v_max3_f32 v240, v240, v72, v73
	v_max3_f32 v240, v240, v74, v75
	v_max3_f32 v240, v240, v76, v77
	v_max3_f32 v240, v240, v78, v79
	s_waitcnt lgkmcnt(12)
	v_mfma_f32_32x32x16_bf16 v[34:49], v[106:109], v[122:125], v[34:49]
	ds_read_b64_tr_b16 v[118:119], v202 offset:0x1400
	ds_read_b64_tr_b16 v[120:121], v202 offset:0x1c00
	v_max3_f32 v240, v240, v80, v81
	v_max3_f32 v240, v240, v82, v83
	v_max3_f32 v240, v240, v84, v85
	v_mov_b32_e32 v241, v240
	s_waitcnt lgkmcnt(12)
	v_mfma_f32_32x32x16_bf16 v[34:49], v[110:113], v[126:129], v[34:49]
	ds_read_b64_tr_b16 v[122:123], v202 offset:0x2400
	ds_read_b64_tr_b16 v[124:125], v202 offset:0x2c00
	s_nop 1
	v_permlane32_swap_b32_e32 v240, v241
	v_max_f32_e32 v240, v240, v241
	v_sub_f32_e32 v241, v240, v252
	v_mul_f32_e32 v241, 0x3db504f3, v241
	s_waitcnt lgkmcnt(12)
	v_mfma_f32_32x32x16_bf16 v[50:65], v[102:105], v[182:185], v[50:65]
	ds_read_b64_tr_b16 v[126:127], v202 offset:0x3400
	ds_read_b64_tr_b16 v[128:129], v202 offset:0x3c00
	v_cmp_ge_f32_e32 vcc, s86, v241
	s_cmp_eq_u64 vcc, exec
	s_cselect_b64 s[4:5], -1, 0
	v_mov_b32_e32 v225, 1.0
	s_cbranch_scc0 .Lh1_rare
; template <int VB, bool SK>
; __device__ __forceinline__ void pv_tile(f32x16* o, int vb0, bf16x8 pa0, bf16x8 pa1, bf16x8 pa2, bf16x8 pa3, bool act) {
;     ...
;     PV_D0(0); PV_D0(1); PV_D0(2); PV_D0(3);
.Lh1_back:
	v_fmamk_f32 v228, v86, 0x3e0293ee, v253
	v_fmamk_f32 v229, v87, 0x3e0293ee, v253
	s_waitcnt lgkmcnt(12)
	v_mfma_f32_32x32x16_bf16 v[50:65], v[66:69], v[186:189], v[50:65]
	ds_read_b64_tr_b16 v[182:183], v202 offset:0x600
	ds_read_b64_tr_b16 v[184:185], v202 offset:0xe00
	v_fmamk_f32 v230, v88, 0x3e0293ee, v253
	v_fmamk_f32 v231, v89, 0x3e0293ee, v253
	v_fmamk_f32 v232, v90, 0x3e0293ee, v253
	s_waitcnt lgkmcnt(12)
	v_mfma_f32_32x32x16_bf16 v[50:65], v[106:109], v[190:193], v[50:65]
	ds_read_b64_tr_b16 v[186:187], v202 offset:0x1600
	ds_read_b64_tr_b16 v[188:189], v202 offset:0x1e00
	v_fmamk_f32 v233, v91, 0x3e0293ee, v253
	v_fmamk_f32 v234, v92, 0x3e0293ee, v253
	v_fmamk_f32 v235, v93, 0x3e0293ee, v253
	s_waitcnt lgkmcnt(12)
	v_mfma_f32_32x32x16_bf16 v[50:65], v[110:113], v[244:247], v[50:65]
	ds_read_b64_tr_b16 v[190:191], v202 offset:0x2600
	ds_read_b64_tr_b16 v[192:193], v202 offset:0x2e00
	v_fmamk_f32 v236, v94, 0x3e0293ee, v253
	v_fmamk_f32 v237, v95, 0x3e0293ee, v253
	v_fmamk_f32 v238, v96, 0x3e0293ee, v253
	s_waitcnt lgkmcnt(12)
	v_mfma_f32_32x32x16_bf16 v[18:33], v[102:105], v[114:117], v[18:33]
	ds_read_b64_tr_b16 v[244:245], v202 offset:0x3600
	ds_read_b64_tr_b16 v[246:247], v202 offset:0x3e00
	v_fmamk_f32 v239, v97, 0x3e0293ee, v253
	v_fmamk_f32 v98, v98, 0x3e0293ee, v253
	v_fmamk_f32 v99, v99, 0x3e0293ee, v253
	s_waitcnt lgkmcnt(12)
	v_mfma_f32_32x32x16_bf16 v[18:33], v[66:69], v[118:121], v[18:33]
	v_fmamk_f32 v100, v100, 0x3e0293ee, v253
	v_fmamk_f32 v101, v101, 0x3e0293ee, v253
	v_fmamk_f32 v86, v70, 0x3e0293ee, v253
	s_waitcnt lgkmcnt(10)
	v_mfma_f32_32x32x16_bf16 v[18:33], v[106:109], v[122:125], v[18:33]
	v_fmamk_f32 v95, v71, 0x3e0293ee, v253
	v_fmamk_f32 v96, v72, 0x3e0293ee, v253
	v_fmamk_f32 v97, v73, 0x3e0293ee, v253
	s_waitcnt lgkmcnt(8)
	v_mfma_f32_32x32x16_bf16 v[18:33], v[110:113], v[126:129], v[18:33]
	v_fmamk_f32 v179, v74, 0x3e0293ee, v253
	v_fmamk_f32 v87, v75, 0x3e0293ee, v253
	v_fmamk_f32 v88, v76, 0x3e0293ee, v253
	s_waitcnt lgkmcnt(0)
	s_barrier
	s_waitcnt vmcnt(0)
	v_mfma_f32_32x32x16_bf16 v[2:17], v[102:105], v[182:185], v[2:17]
	ds_write_b128 v209, v[162:165]
	v_fmamk_f32 v89, v77, 0x3e0293ee, v253
	v_fmamk_f32 v90, v78, 0x3e0293ee, v253
	v_fmamk_f32 v91, v79, 0x3e0293ee, v253
	v_mfma_f32_32x32x16_bf16 v[2:17], v[66:69], v[186:189], v[2:17]
	ds_write_b128 v210, v[166:169]
	v_fmamk_f32 v92, v80, 0x3e0293ee, v253
	v_fmamk_f32 v93, v81, 0x3e0293ee, v253
	v_fmamk_f32 v94, v82, 0x3e0293ee, v253
	v_mfma_f32_32x32x16_bf16 v[2:17], v[106:109], v[190:193], v[2:17]
	ds_write_b128 v217, v[170:173] offset:32768
	v_fmamk_f32 v180, v83, 0x3e0293ee, v253
	v_fmamk_f32 v181, v84, 0x3e0293ee, v253
	v_fmamk_f32 v178, v85, 0x3e0293ee, v253
	v_mfma_f32_32x32x16_bf16 v[2:17], v[110:113], v[244:247], v[2:17]
	ds_write_b128 v217, v[174:177] offset:40960
	s_and_b64 vcc, exec, s[4:5]
	s_cbranch_vccnz .Lh1_noresc
	s_and_saveexec_b64 s[52:53], s[0:1]
	ds_write_b32 v219, v225 offset:128
	s_or_b64 exec, exec, s[52:53]
	s_waitcnt lgkmcnt(0)
	ds_read_b128 v[102:105], v218 offset:224
	ds_read_b128 v[106:109], v218 offset:192
	ds_read_b128 v[110:113], v218 offset:160
	ds_read_b128 v[114:117], v218 offset:128
	s_waitcnt lgkmcnt(3)
	v_pk_mul_f32 v[48:49], v[48:49], v[104:105]
	s_waitcnt lgkmcnt(2)
	v_pk_mul_f32 v[44:45], v[44:45], v[108:109]
	s_waitcnt lgkmcnt(1)
	v_pk_mul_f32 v[40:41], v[40:41], v[112:113]
	s_waitcnt lgkmcnt(0)
	v_pk_mul_f32 v[36:37], v[36:37], v[116:117]
	v_pk_mul_f32 v[46:47], v[46:47], v[102:103]
	v_pk_mul_f32 v[42:43], v[42:43], v[106:107]
	v_pk_mul_f32 v[38:39], v[38:39], v[110:111]
	v_pk_mul_f32 v[34:35], v[34:35], v[114:115]
	v_pk_mul_f32 v[64:65], v[64:65], v[104:105]
	v_pk_mul_f32 v[60:61], v[60:61], v[108:109]
	v_pk_mul_f32 v[56:57], v[56:57], v[112:113]
	v_pk_mul_f32 v[52:53], v[52:53], v[116:117]
	v_pk_mul_f32 v[62:63], v[62:63], v[102:103]
	v_pk_mul_f32 v[58:59], v[58:59], v[106:107]
	v_pk_mul_f32 v[54:55], v[54:55], v[110:111]
	v_pk_mul_f32 v[50:51], v[50:51], v[114:115]
	v_pk_mul_f32 v[32:33], v[32:33], v[104:105]
	v_pk_mul_f32 v[28:29], v[28:29], v[108:109]
	v_pk_mul_f32 v[24:25], v[24:25], v[112:113]
	v_pk_mul_f32 v[20:21], v[20:21], v[116:117]
	v_pk_mul_f32 v[30:31], v[30:31], v[102:103]
	v_pk_mul_f32 v[26:27], v[26:27], v[106:107]
	v_pk_mul_f32 v[22:23], v[22:23], v[110:111]
	v_pk_mul_f32 v[18:19], v[18:19], v[114:115]
	v_pk_mul_f32 v[16:17], v[16:17], v[104:105]
	v_pk_mul_f32 v[12:13], v[12:13], v[108:109]
	v_pk_mul_f32 v[8:9], v[8:9], v[112:113]
	v_pk_mul_f32 v[4:5], v[4:5], v[116:117]
	v_pk_mul_f32 v[14:15], v[14:15], v[102:103]
	v_pk_mul_f32 v[10:11], v[10:11], v[106:107]
	v_pk_mul_f32 v[6:7], v[6:7], v[110:111]
	v_pk_mul_f32 v[2:3], v[2:3], v[114:115]

; __device__ __forceinline__ void mask_tile(f32x16& p0, f32x16& p1, int dq, unsigned W) {
;     const float NEG = -__builtin_inff();
; #pragma unroll
;     for (int r = 0; r < 16; ++r) {
;         const int c = (r & 3) + 8 * (r >> 2);
;         if ((unsigned)(dq - c) >= W) p0[r] = NEG;
;         if ((unsigned)(dq - c - 32) >= W) p1[r] = NEG;
;     }
; }
.LBB0_1137:
	s_sub_i32 s27, s26, 63
	s_cmp_le_i32 s26, s13
	s_cselect_b64 s[4:5], -1, 0
	s_cmp_gt_i32 s27, s15
	s_cselect_b64 s[52:53], -1, 0
	s_and_b64 s[4:5], s[4:5], s[52:53]
	s_and_b64 vcc, exec, s[4:5]
	ds_read_b64_tr_b16 v[230:231], v202 offset:0x4000
	ds_read_b64_tr_b16 v[232:233], v202 offset:0x4800
	ds_read_b64_tr_b16 v[234:235], v202 offset:0x5000
	ds_read_b64_tr_b16 v[236:237], v202 offset:0x5800
	ds_read_b64_tr_b16 v[238:239], v202 offset:0x6000
	ds_read_b64_tr_b16 v[240:241], v202 offset:0x6800
	ds_read_b64_tr_b16 v[242:243], v202 offset:0x7000
	ds_read_b64_tr_b16 v[244:245], v202 offset:0x7800
	ds_read_b64_tr_b16 v[86:87], v202 offset:0x4200
	ds_read_b64_tr_b16 v[88:89], v202 offset:0x4a00
	ds_read_b64_tr_b16 v[90:91], v202 offset:0x5200
	ds_read_b64_tr_b16 v[92:93], v202 offset:0x5a00
	ds_read_b64_tr_b16 v[94:95], v202 offset:0x6200
	ds_read_b64_tr_b16 v[96:97], v202 offset:0x6a00
	s_cbranch_vccnz .Lh2_nomask
	v_add_u32_e32 v226, s80, v222
	v_add_u32_e32 v66, 0xffffff80, v226
	v_cmp_gt_u32_e32 vcc, s85, v66
	v_add_u32_e32 v66, 0xffffff60, v226
	s_nop 0
	v_cndmask_b32_e32 v114, v215, v114, vcc
	v_cmp_gt_u32_e32 vcc, s85, v66
	v_add_u32_e32 v66, 0xffffff7f, v226
	s_nop 0
	v_cndmask_b32_e32 v98, v215, v98, vcc
	v_cmp_gt_u32_e32 vcc, s85, v66
	v_add_u32_e32 v66, 0xffffff5f, v226
	s_nop 0
	v_cndmask_b32_e32 v115, v215, v115, vcc
	v_cmp_gt_u32_e32 vcc, s85, v66
	v_add_u32_e32 v66, 0xffffff7e, v226
	s_nop 0
	v_cndmask_b32_e32 v99, v215, v99, vcc
	v_cmp_gt_u32_e32 vcc, s85, v66
	v_add_u32_e32 v66, 0xffffff5e, v226
	s_nop 0
	v_cndmask_b32_e32 v116, v215, v116, vcc
	v_cmp_gt_u32_e32 vcc, s85, v66
	v_add_u32_e32 v66, 0xffffff7d, v226
	s_nop 0
	v_cndmask_b32_e32 v100, v215, v100, vcc
	v_cmp_gt_u32_e32 vcc, s85, v66
	v_add_u32_e32 v66, 0xffffff5d, v226
	s_nop 0
	v_cndmask_b32_e32 v117, v215, v117, vcc
	v_cmp_gt_u32_e32 vcc, s85, v66
	v_add_u32_e32 v66, 0xffffff78, v226
	s_nop 0
	v_cndmask_b32_e32 v101, v215, v101, vcc
	v_cmp_gt_u32_e32 vcc, s85, v66
	v_add_u32_e32 v66, 0xffffff58, v226
	s_nop 0
	v_cndmask_b32_e32 v118, v215, v118, vcc
	v_cmp_gt_u32_e32 vcc, s85, v66
	v_add_u32_e32 v66, 0xffffff77, v226
	s_nop 0
	v_cndmask_b32_e32 v102, v215, v102, vcc
	v_cmp_gt_u32_e32 vcc, s85, v66
	v_add_u32_e32 v66, 0xffffff57, v226
	s_nop 0
	v_cndmask_b32_e32 v119, v215, v119, vcc
	v_cmp_gt_u32_e32 vcc, s85, v66
	v_add_u32_e32 v66, 0xffffff76, v226
	s_nop 0
	v_cndmask_b32_e32 v103, v215, v103, vcc
	v_cmp_gt_u32_e32 vcc, s85, v66
	v_add_u32_e32 v66, 0xffffff56, v226
	s_nop 0
	v_cndmask_b32_e32 v120, v215, v120, vcc
	v_cmp_gt_u32_e32 vcc, s85, v66
	v_add_u32_e32 v66, 0xffffff75, v226
	s_nop 0
	v_cndmask_b32_e32 v104, v215, v104, vcc
	v_cmp_gt_u32_e32 vcc, s85, v66
	v_add_u32_e32 v66, 0xffffff55, v226
	s_nop 0
	v_cndmask_b32_e32 v121, v215, v121, vcc
	v_cmp_gt_u32_e32 vcc, s85, v66
	v_add_u32_e32 v66, 0xffffff70, v226
	s_nop 0
	v_cndmask_b32_e32 v105, v215, v105, vcc
	v_cmp_gt_u32_e32 vcc, s85, v66
	v_add_u32_e32 v66, 0xffffff50, v226
	s_nop 0
	v_cndmask_b32_e32 v122, v215, v122, vcc
	v_cmp_gt_u32_e32 vcc, s85, v66
	v_add_u32_e32 v66, 0xffffff6f, v226
	s_nop 0
	v_cndmask_b32_e32 v106, v215, v106, vcc
	v_cmp_gt_u32_e32 vcc, s85, v66
	v_add_u32_e32 v66, 0xffffff4f, v226
	s_nop 0
	v_cndmask_b32_e32 v123, v215, v123, vcc
	v_cmp_gt_u32_e32 vcc, s85, v66
	v_add_u32_e32 v66, 0xffffff6e, v226
	s_nop 0
	v_cndmask_b32_e32 v107, v215, v107, vcc
	v_cmp_gt_u32_e32 vcc, s85, v66
	v_add_u32_e32 v66, 0xffffff4e, v226
	s_nop 0
	v_cndmask_b32_e32 v124, v215, v124, vcc
	v_cmp_gt_u32_e32 vcc, s85, v66
	v_add_u32_e32 v66, 0xffffff6d, v226
	s_nop 0
	v_cndmask_b32_e32 v108, v215, v108, vcc
	v_cmp_gt_u32_e32 vcc, s85, v66
	v_add_u32_e32 v66, 0xffffff4d, v226
	s_nop 0
	v_cndmask_b32_e32 v125, v215, v125, vcc
	v_cmp_gt_u32_e32 vcc, s85, v66
	v_add_u32_e32 v66, 0xffffff68, v226
	s_nop 0
	v_cndmask_b32_e32 v109, v215, v109, vcc
	v_cmp_gt_u32_e32 vcc, s85, v66
	v_add_u32_e32 v66, 0xffffff48, v226
	s_nop 0
	v_cndmask_b32_e32 v126, v215, v126, vcc
	v_cmp_gt_u32_e32 vcc, s85, v66
	v_add_u32_e32 v66, 0xffffff67, v226
	s_nop 0
	v_cndmask_b32_e32 v110, v215, v110, vcc
	v_cmp_gt_u32_e32 vcc, s85, v66
	v_add_u32_e32 v66, 0xffffff47, v226
	s_nop 0
	v_cndmask_b32_e32 v127, v215, v127, vcc
	v_cmp_gt_u32_e32 vcc, s85, v66
	v_add_u32_e32 v66, 0xffffff66, v226
	s_nop 0
	v_cndmask_b32_e32 v111, v215, v111, vcc
	v_cmp_gt_u32_e32 vcc, s85, v66
	v_add_u32_e32 v66, 0xffffff46, v226
	s_nop 0
	v_cndmask_b32_e32 v128, v215, v128, vcc
	v_cmp_gt_u32_e32 vcc, s85, v66
	v_add_u32_e32 v66, 0xffffff65, v226
	s_nop 0
	v_cndmask_b32_e32 v112, v215, v112, vcc
	v_cmp_gt_u32_e32 vcc, s85, v66
	v_add_u32_e32 v66, 0xffffff45, v226
	s_nop 0
	v_cndmask_b32_e32 v129, v215, v129, vcc
	v_cmp_gt_u32_e32 vcc, s85, v66
	s_nop 1
	v_cndmask_b32_e32 v113, v215, v113, vcc
; __device__ __forceinline__ void partialSM(f32x16& p0, f32x16& p1, float& m_reg, float& mn, float& alpha) {
;     float pmax = p0[0]; for (int r = 1; r < 16; ++r) pmax = fmaxf(pmax, p0[r]); for (int r = 0; r < 16; ++r) pmax = fmaxf(pmax, p1[r]);
;     { auto rr = __builtin_amdgcn_permlane32_swap(__float_as_uint(pmax), __float_as_uint(pmax), false, false);
;       pmax = fmaxf(__uint_as_float(rr[0]), __uint_as_float(rr[1])); }
;     constexpr float C2 = 1.4426950408889634f * SCALE;
;     if (__builtin_expect(__all((pmax - m_reg) * SCALE <= THR), 1)) { mn = m_reg; alpha = 1.f; }
;     else { mn = fmaxf(m_reg, pmax); alpha = __builtin_amdgcn_exp2f((m_reg - mn) * C2); m_reg = mn; }
;     const float mnL = -mn * C2;
;     for (int r = 0; r < 16; ++r) p0[r] = fmaf(p0[r], C2, mnL); for (int r = 0; r < 16; ++r) p1[r] = fmaf(p1[r], C2, mnL);
.Lh2_nomask:
	v_max_f32_e32 v66, v114, v115
	v_max3_f32 v66, v66, v116, v117
	v_max3_f32 v66, v66, v118, v119
	v_max3_f32 v66, v66, v120, v121
	v_max3_f32 v66, v66, v122, v123
	s_waitcnt lgkmcnt(12)
	v_mfma_f32_32x32x16_bf16 v[34:49], v[178:181], v[230:233], v[34:49]
	ds_read_b64_tr_b16 v[246:247], v202 offset:0x7200
	ds_read_b64_tr_b16 v[248:249], v202 offset:0x7a00
	v_max3_f32 v66, v66, v124, v125
	v_max3_f32 v66, v66, v126, v127
	v_max3_f32 v66, v66, v128, v129
	v_max3_f32 v66, v66, v98, v99
	s_waitcnt lgkmcnt(12)
	v_mfma_f32_32x32x16_bf16 v[34:49], v[182:185], v[234:237], v[34:49]
	ds_read_b64_tr_b16 v[230:231], v202 offset:0x4400
	ds_read_b64_tr_b16 v[232:233], v202 offset:0x4c00
	v_max3_f32 v66, v66, v100, v101
	v_max3_f32 v66, v66, v102, v103
	v_max3_f32 v66, v66, v104, v105
	v_max3_f32 v66, v66, v106, v107
	s_waitcnt lgkmcnt(12)
	v_mfma_f32_32x32x16_bf16 v[34:49], v[186:189], v[238:241], v[34:49]
	ds_read_b64_tr_b16 v[234:235], v202 offset:0x5400
	ds_read_b64_tr_b16 v[236:237], v202 offset:0x5c00
	v_max3_f32 v66, v66, v108, v109
	v_max3_f32 v66, v66, v110, v111
	v_max3_f32 v66, v66, v112, v113
	v_mov_b32_e32 v67, v66
	s_waitcnt lgkmcnt(12)
	v_mfma_f32_32x32x16_bf16 v[34:49], v[190:193], v[242:245], v[34:49]
	ds_read_b64_tr_b16 v[238:239], v202 offset:0x6400
	ds_read_b64_tr_b16 v[240:241], v202 offset:0x6c00
	s_nop 1
	v_permlane32_swap_b32_e32 v66, v67
	v_max_f32_e32 v66, v66, v67
	v_sub_f32_e32 v67, v66, v252
	v_mul_f32_e32 v67, 0x3db504f3, v67
	s_waitcnt lgkmcnt(12)
	v_mfma_f32_32x32x16_bf16 v[50:65], v[178:181], v[86:89], v[50:65]
	ds_read_b64_tr_b16 v[242:243], v202 offset:0x7400
	ds_read_b64_tr_b16 v[244:245], v202 offset:0x7c00
	v_cmp_ge_f32_e32 vcc, s86, v67
	s_cmp_eq_u64 vcc, exec
	s_cselect_b64 s[4:5], -1, 0
	v_mov_b32_e32 v254, 1.0
	s_cbranch_scc0 .Lh2_rare
.Lh2_back:
	v_fmamk_f32 v68, v114, 0x3e0293ee, v253
	v_fmamk_f32 v69, v115, 0x3e0293ee, v253
	s_waitcnt lgkmcnt(12)
	v_mfma_f32_32x32x16_bf16 v[50:65], v[182:185], v[90:93], v[50:65]
	ds_read_b64_tr_b16 v[86:87], v202 offset:0x4600
	ds_read_b64_tr_b16 v[88:89], v202 offset:0x4e00
	v_fmamk_f32 v70, v116, 0x3e0293ee, v253
	v_fmamk_f32 v71, v117, 0x3e0293ee, v253
	v_fmamk_f32 v79, v118, 0x3e0293ee, v253
	v_fmamk_f32 v80, v119, 0x3e0293ee, v253
	s_waitcnt lgkmcnt(12)
	v_mfma_f32_32x32x16_bf16 v[50:65], v[186:189], v[94:97], v[50:65]
	ds_read_b64_tr_b16 v[90:91], v202 offset:0x5600
	ds_read_b64_tr_b16 v[92:93], v202 offset:0x5e00
	v_fmamk_f32 v72, v120, 0x3e0293ee, v253
	v_fmamk_f32 v73, v121, 0x3e0293ee, v253
	v_fmamk_f32 v81, v122, 0x3e0293ee, v253
	v_fmamk_f32 v82, v123, 0x3e0293ee, v253
	s_waitcnt lgkmcnt(12)
	v_mfma_f32_32x32x16_bf16 v[50:65], v[190:193], v[246:249], v[50:65]
	ds_read_b64_tr_b16 v[94:95], v202 offset:0x6600
	ds_read_b64_tr_b16 v[96:97], v202 offset:0x6e00
	v_fmamk_f32 v74, v124, 0x3e0293ee, v253
	v_fmamk_f32 v75, v125, 0x3e0293ee, v253
	v_fmamk_f32 v76, v126, 0x3e0293ee, v253
	v_fmamk_f32 v77, v127, 0x3e0293ee, v253
	s_waitcnt lgkmcnt(12)
	v_mfma_f32_32x32x16_bf16 v[18:33], v[178:181], v[230:233], v[18:33]
	ds_read_b64_tr_b16 v[246:247], v202 offset:0x7600
	ds_read_b64_tr_b16 v[248:249], v202 offset:0x7e00
	v_fmamk_f32 v83, v128, 0x3e0293ee, v253
	v_fmamk_f32 v78, v129, 0x3e0293ee, v253
	v_fmamk_f32 v126, v98, 0x3e0293ee, v253
	v_fmamk_f32 v127, v99, 0x3e0293ee, v253
	s_waitcnt lgkmcnt(12)
	v_mfma_f32_32x32x16_bf16 v[18:33], v[182:185], v[234:237], v[18:33]
	v_fmamk_f32 v124, v100, 0x3e0293ee, v253
	v_fmamk_f32 v125, v101, 0x3e0293ee, v253
	v_fmamk_f32 v120, v102, 0x3e0293ee, v253
	s_waitcnt lgkmcnt(10)
	v_mfma_f32_32x32x16_bf16 v[18:33], v[186:189], v[238:241], v[18:33]
	v_fmamk_f32 v121, v103, 0x3e0293ee, v253
	v_fmamk_f32 v116, v104, 0x3e0293ee, v253
	v_fmamk_f32 v117, v105, 0x3e0293ee, v253
	s_waitcnt lgkmcnt(8)
	v_mfma_f32_32x32x16_bf16 v[18:33], v[190:193], v[242:245], v[18:33]
	v_fmamk_f32 v114, v106, 0x3e0293ee, v253
	v_fmamk_f32 v115, v107, 0x3e0293ee, v253
	v_fmamk_f32 v128, v108, 0x3e0293ee, v253
	s_waitcnt lgkmcnt(0)
	s_andn2_b64 vcc, exec, s[76:77]
	s_barrier
	s_cbranch_vccnz .Lh2_pvt_nowrite
	s_waitcnt vmcnt(0)
	v_mfma_f32_32x32x16_bf16 v[2:17], v[178:181], v[86:89], v[2:17]
	ds_write_b128 v209, v[162:165] offset:16384
	v_fmamk_f32 v129, v109, 0x3e0293ee, v253
	v_fmamk_f32 v122, v110, 0x3e0293ee, v253
	v_fmamk_f32 v123, v111, 0x3e0293ee, v253
	v_mfma_f32_32x32x16_bf16 v[2:17], v[182:185], v[90:93], v[2:17]
	ds_write_b128 v210, v[166:169] offset:16384
	v_fmamk_f32 v118, v112, 0x3e0293ee, v253
	v_fmamk_f32 v119, v113, 0x3e0293ee, v253
	v_add_f32_e32 v98, v223, v224
	v_mfma_f32_32x32x16_bf16 v[2:17], v[186:189], v[94:97], v[2:17]
	ds_write_b128 v217, v[170:173] offset:49152
	v_fmac_f32_e32 v98, v197, v221
	v_add_f32_e32 v221, v228, v229
	v_fmac_f32_e32 v221, v98, v225
	v_mfma_f32_32x32x16_bf16 v[2:17], v[190:193], v[246:249], v[2:17]
	ds_write_b128 v217, v[174:177] offset:57344
	s_branch .Lh2_pvt_join
; template <class TIn, class TOut>
; __device__ __forceinline__ void causal_swa_block(const BlockRef<TIn, TOut>& cur, const BlockRef<TIn, TOut>& nxt, int skv, int W, char* lds, Seam<TIn>& S) {
;     ...
;     for (int t = 1; t + 1 < NT; t += 2) {
.Lh2_pvt_nowrite:
	v_mfma_f32_32x32x16_bf16 v[2:17], v[178:181], v[86:89], v[2:17]
	v_fmamk_f32 v129, v109, 0x3e0293ee, v253
	v_fmamk_f32 v122, v110, 0x3e0293ee, v253
	v_fmamk_f32 v123, v111, 0x3e0293ee, v253
	v_mfma_f32_32x32x16_bf16 v[2:17], v[182:185], v[90:93], v[2:17]
	v_fmamk_f32 v118, v112, 0x3e0293ee, v253
	v_fmamk_f32 v119, v113, 0x3e0293ee, v253
	v_add_f32_e32 v98, v223, v224
	v_mfma_f32_32x32x16_bf16 v[2:17], v[186:189], v[94:97], v[2:17]
	v_fmac_f32_e32 v98, v197, v221
	v_add_f32_e32 v221, v228, v229
	v_fmac_f32_e32 v221, v98, v225
	v_mfma_f32_32x32x16_bf16 v[2:17], v[190:193], v[246:249], v[2:17]
.Lh2_pvt_join:
.Lh2_nowrite:
	v_add_u32_e32 v194, 0x4000, v194
	v_add_u32_e32 v222, 0xffffff80, v222
	v_add_u32_e32 v255, 0x8000, v255
	s_addk_i32 s26, 0x80
	s_add_i32 s25, s25, 2
	s_and_b64 vcc, exec, s[4:5]
	s_cbranch_vccnz .Lh2_noresc
	s_and_saveexec_b64 s[52:53], s[0:1]
	ds_write_b32 v219, v254 offset:128
	s_or_b64 exec, exec, s[52:53]
	s_waitcnt lgkmcnt(0)
	ds_read_b128 v[164:167], v218 offset:224
	ds_read_b128 v[168:171], v218 offset:192
	ds_read_b128 v[172:175], v218 offset:160
	ds_read_b128 v[180:183], v218 offset:128
	s_waitcnt lgkmcnt(3)
	v_pk_mul_f32 v[48:49], v[48:49], v[166:167]
	s_waitcnt lgkmcnt(2)
	v_pk_mul_f32 v[44:45], v[44:45], v[170:171]
	s_waitcnt lgkmcnt(1)
	v_pk_mul_f32 v[40:41], v[40:41], v[174:175]
	s_waitcnt lgkmcnt(0)
	v_pk_mul_f32 v[36:37], v[36:37], v[182:183]
	v_pk_mul_f32 v[46:47], v[46:47], v[164:165]
	v_pk_mul_f32 v[42:43], v[42:43], v[168:169]
	v_pk_mul_f32 v[38:39], v[38:39], v[172:173]
	v_pk_mul_f32 v[34:35], v[34:35], v[180:181]
	v_pk_mul_f32 v[64:65], v[64:65], v[166:167]
	v_pk_mul_f32 v[60:61], v[60:61], v[170:171]
	v_pk_mul_f32 v[56:57], v[56:57], v[174:175]
	v_pk_mul_f32 v[52:53], v[52:53], v[182:183]
	v_pk_mul_f32 v[62:63], v[62:63], v[164:165]
	v_pk_mul_f32 v[58:59], v[58:59], v[168:169]
	v_pk_mul_f32 v[54:55], v[54:55], v[172:173]
	v_pk_mul_f32 v[50:51], v[50:51], v[180:181]
	v_pk_mul_f32 v[32:33], v[32:33], v[166:167]
	v_pk_mul_f32 v[28:29], v[28:29], v[170:171]
	v_pk_mul_f32 v[24:25], v[24:25], v[174:175]
	v_pk_mul_f32 v[20:21], v[20:21], v[182:183]
	v_pk_mul_f32 v[30:31], v[30:31], v[164:165]
	v_pk_mul_f32 v[26:27], v[26:27], v[168:169]
	v_pk_mul_f32 v[22:23], v[22:23], v[172:173]
	v_pk_mul_f32 v[18:19], v[18:19], v[180:181]
	v_pk_mul_f32 v[16:17], v[16:17], v[166:167]
	v_pk_mul_f32 v[12:13], v[12:13], v[170:171]
	v_pk_mul_f32 v[8:9], v[8:9], v[174:175]
	v_pk_mul_f32 v[4:5], v[4:5], v[182:183]
	v_pk_mul_f32 v[14:15], v[14:15], v[164:165]
	v_pk_mul_f32 v[10:11], v[10:11], v[168:169]
	v_pk_mul_f32 v[6:7], v[6:7], v[172:173]
	v_pk_mul_f32 v[2:3], v[2:3], v[180:181]
